# prologue and layer-1 rmsnorm row loops: the 4 gain loads (and the 4 residual loads) of a row issued together instead of one round trip each
# speedup vs baseline: 1.0443x; 1.0107x over previous
; #define GAS __attribute__((address_space(1)))
; __device__ __forceinline__ unsigned cvt_pk_bf16(float lo, float hi) { const f32x2 v = {lo, hi}; return __builtin_bit_cast(unsigned, __builtin_convertvector(v, bf16n2)); }
; __device__ __forceinline__ float frsq(float x) { return __builtin_amdgcn_rsqf(x); }
; __device__ __forceinline__ void xn_row(const GAS float* src, GAS float* hdst, const GAS float* g, GAS bf16* xnrow, int lane) {
;     const GAS f32x4* xr = (const GAS f32x4*)src + lane;
;     f32x4 v[4]; float s = 0.f;
; #pragma unroll
;     for (int j = 0; j < 4; ++j) { v[j] = xr[64 * j]; s += (v[j].x * v[j].x + v[j].y * v[j].y) + (v[j].z * v[j].z + v[j].w * v[j].w); }
;     if (hdst) { GAS v2u* ho = (GAS v2u*)hdst + lane;
; #pragma unroll
;         for (int j = 0; j < 4; ++j) { v2u o; o.x = cvt_pk_bf16(v[j].x, v[j].y); o.y = cvt_pk_bf16(v[j].z, v[j].w); ho[64 * j] = o; } }
;     const float rs = frsq(wave_sum(s) * (1.f / D) + EPS);
;     GAS v2u* o8 = (GAS v2u*)xnrow + lane;
; #pragma unroll
;     for (int j = 0; j < 4; ++j) { const f32x4 gg = ((const GAS f32x4*)g)[lane + 64 * j]; v2u o; o.x = cvt_pk_bf16(v[j].x * rs * gg.x, v[j].y * rs * gg.y); o.y = cvt_pk_bf16(v[j].z * rs * gg.z, v[j].w * rs * gg.w); o8[64 * j] = o; }
.LBB0_42:
	v_mov_b32_e32 v0, s41
	v_mov_b32_e32 v1, s42
	ds_read_b64 v[4:5], v0
	ds_read_b64 v[28:29], v1
	v_mov_b32_e32 v0, 0
	s_lshl_b64 s[22:23], s[24:25], 12
	v_mbcnt_lo_u32_b32 v0, -1, v0
	v_mbcnt_hi_u32_b32 v30, -1, v0
	s_add_u32 s20, s20, s22
	v_ashrrev_i32_e32 v31, 31, v30
	s_addc_u32 s21, s21, s23
	v_lshlrev_b64 v[32:33], 4, v[30:31]
	v_lshl_add_u64 v[34:35], s[20:21], 0, v[32:33]
	global_load_dwordx4 v[16:19], v[34:35], off
	global_load_dwordx4 v[20:23], v[34:35], off offset:1024
	global_load_dwordx4 v[24:27], v[34:35], off offset:2048
	global_load_dwordx4 v[0:3], v[34:35], off offset:3072
	v_lshlrev_b64 v[34:35], 3, v[30:31]
	s_waitcnt lgkmcnt(1)
	v_readfirstlane_b32 s23, v5
	v_readfirstlane_b32 s22, v4
	s_waitcnt lgkmcnt(0)
	v_readfirstlane_b32 s21, v29
	v_readfirstlane_b32 s20, v28
	v_lshl_add_u64 v[4:5], s[22:23], 0, v[34:35]
	v_lshl_add_u64 v[4:5], v[4:5], 0, s[6:7]
	v_lshl_add_u64 v[4:5], v[4:5], 0, s[16:17]
	v_add_co_u32_e32 v4, vcc, s43, v4
	v_lshl_add_u64 v[32:33], s[20:21], 0, v[32:33]
	s_nop 0
	v_addc_co_u32_e32 v5, vcc, 0, v5, vcc
	global_load_dwordx4 v[52:55], v[32:33], off
	global_load_dwordx4 v[56:59], v[32:33], off offset:1024
	global_load_dwordx4 v[60:63], v[32:33], off offset:2048
	global_load_dwordx4 v[64:67], v[32:33], off offset:3072
	v_cmp_lt_i32_e32 vcc, v8, v7
	s_add_u32 s20, s35, s6
	s_addc_u32 s21, s31, s7
	s_waitcnt vmcnt(7)
	v_cvt_pk_bf16_f32 v28, v16, v17
	v_cvt_pk_bf16_f32 v29, v18, v19
	s_waitcnt vmcnt(6)
	v_cvt_pk_bf16_f32 v30, v20, v21
	v_cvt_pk_bf16_f32 v31, v22, v23
	s_waitcnt vmcnt(5)
	v_cvt_pk_bf16_f32 v36, v24, v25
	v_cvt_pk_bf16_f32 v37, v26, v27
	s_waitcnt vmcnt(4)
	v_cvt_pk_bf16_f32 v38, v0, v1
	v_cvt_pk_bf16_f32 v39, v2, v3
	global_store_dwordx2 v[4:5], v[28:29], off
	global_store_dwordx2 v[4:5], v[30:31], off offset:512
	global_store_dwordx2 v[4:5], v[36:37], off offset:1024
	global_store_dwordx2 v[4:5], v[38:39], off offset:1536
	v_cndmask_b32_e32 v4, v6, v8, vcc
	v_lshlrev_b32_e32 v15, 2, v4
	v_pk_mul_f32 v[4:5], v[18:19], v[18:19]
	v_pk_mul_f32 v[36:37], v[16:17], v[16:17]
	v_pk_mul_f32 v[38:39], v[22:23], v[22:23]
	v_pk_mul_f32 v[40:41], v[20:21], v[20:21]
	v_pk_mov_b32 v[46:47], v[36:37], v[4:5] op_sel:[1,0]
	v_mov_b32_e32 v37, v5
	v_pk_mov_b32 v[4:5], v[40:41], v[38:39] op_sel:[1,0]
	v_mov_b32_e32 v41, v39
	v_mul_f32_e32 v45, v0, v0
	v_mul_f32_e32 v42, v25, v25
	v_mul_f32_e32 v44, v27, v27
	v_pk_add_f32 v[36:37], v[46:47], v[36:37]
	v_pk_add_f32 v[4:5], v[4:5], v[40:41]
	v_mul_f32_e32 v48, v1, v1
	v_mul_f32_e32 v49, v2, v2
	v_mul_f32_e32 v50, v3, v3
	v_pk_fma_f32 v[38:39], v[24:25], v[24:25], v[42:43] op_sel_hi:[1,1,0]
	v_pk_fma_f32 v[42:43], v[26:27], v[26:27], v[44:45] op_sel_hi:[1,1,0]
	v_pk_add_f32 v[36:37], v[36:37], v[36:37] op_sel:[0,1] op_sel_hi:[1,0]
	v_pk_add_f32 v[4:5], v[4:5], v[4:5] op_sel:[0,1] op_sel_hi:[1,0]
	v_mov_b32_e32 v39, v49
	v_mov_b32_e32 v43, v50
	v_mov_b32_e32 v37, v45
	v_mov_b32_e32 v5, v48
	v_pk_add_f32 v[38:39], v[38:39], v[42:43]
	v_pk_add_f32 v[4:5], v[36:37], v[4:5]
	v_cmp_lt_i32_e32 vcc, v9, v7
	v_pk_add_f32 v[4:5], v[4:5], v[38:39]
	s_nop 0
	v_add_f32_e32 v4, v4, v5
	ds_bpermute_b32 v5, v15, v4
	v_cndmask_b32_e32 v15, v6, v9, vcc
	v_lshlrev_b32_e32 v15, 2, v15
	v_cmp_lt_i32_e32 vcc, v10, v7
	s_waitcnt lgkmcnt(0)
	v_add_f32_e32 v4, v4, v5
	ds_bpermute_b32 v5, v15, v4
	v_cndmask_b32_e32 v15, v6, v10, vcc
	v_lshlrev_b32_e32 v15, 2, v15
	v_cmp_lt_i32_e32 vcc, v11, v7
	s_waitcnt lgkmcnt(0)
	v_add_f32_e32 v4, v4, v5
	ds_bpermute_b32 v5, v15, v4
	v_cndmask_b32_e32 v15, v6, v11, vcc
	v_lshlrev_b32_e32 v15, 2, v15
	v_cmp_lt_i32_e32 vcc, v12, v7
	s_waitcnt lgkmcnt(0)
	v_add_f32_e32 v4, v4, v5
	ds_bpermute_b32 v5, v15, v4
	v_cndmask_b32_e32 v15, v6, v12, vcc
	v_lshlrev_b32_e32 v15, 2, v15
	v_cmp_lt_i32_e32 vcc, v13, v7
	s_waitcnt lgkmcnt(0)
	v_add_f32_e32 v4, v4, v5
	ds_bpermute_b32 v5, v15, v4
	v_cndmask_b32_e32 v15, v6, v13, vcc
	v_lshlrev_b32_e32 v15, 2, v15
	s_waitcnt lgkmcnt(0)
	v_add_f32_e32 v36, v4, v5
	ds_bpermute_b32 v15, v15, v36
	v_lshl_add_u64 v[4:5], s[20:21], 0, v[34:35]
	s_mov_b64 s[20:21], 0
	s_waitcnt lgkmcnt(0)
	v_add_f32_e32 v15, v36, v15
	v_fmamk_f32 v15, v15, 0x3a800000, v14
	v_rsq_f32_e32 v34, v15
	v_add_co_u32_e32 v36, vcc, s44, v4
	v_pk_mul_f32 v[16:17], v[16:17], v[34:35] op_sel_hi:[1,0]
	v_pk_mul_f32 v[18:19], v[18:19], v[34:35] op_sel_hi:[1,0]
	v_addc_co_u32_e32 v37, vcc, 0, v5, vcc
	v_pk_mul_f32 v[20:21], v[20:21], v[34:35] op_sel_hi:[1,0]
	v_pk_mul_f32 v[22:23], v[22:23], v[34:35] op_sel_hi:[1,0]
	s_waitcnt vmcnt(4)
	v_pk_mul_f32 v[16:17], v[52:53], v[16:17]
	v_pk_mul_f32 v[18:19], v[54:55], v[18:19]
	v_cvt_pk_bf16_f32 v16, v16, v17
	v_cvt_pk_bf16_f32 v17, v18, v19
	global_store_dwordx2 v[36:37], v[16:17], off
	v_pk_mul_f32 v[0:1], v[0:1], v[34:35] op_sel_hi:[1,0]
	v_pk_mul_f32 v[2:3], v[2:3], v[34:35] op_sel_hi:[1,0]
	v_lshl_add_u64 v[4:5], v[4:5], 0, s[8:9]
	v_pk_mul_f32 v[16:17], v[56:57], v[20:21]
	v_pk_mul_f32 v[18:19], v[58:59], v[22:23]
	v_cvt_pk_bf16_f32 v16, v16, v17
	v_cvt_pk_bf16_f32 v17, v18, v19
	global_store_dwordx2 v[36:37], v[16:17], off offset:512
	v_pk_mul_f32 v[20:21], v[24:25], v[34:35] op_sel_hi:[1,0]
	v_pk_mul_f32 v[22:23], v[26:27], v[34:35] op_sel_hi:[1,0]
	v_pk_mul_f32 v[16:17], v[20:21], v[60:61]
	v_pk_mul_f32 v[18:19], v[22:23], v[62:63]
	v_cvt_pk_bf16_f32 v16, v16, v17
	v_cvt_pk_bf16_f32 v17, v18, v19
	global_store_dwordx2 v[36:37], v[16:17], off offset:1024
	v_pk_mul_f32 v[0:1], v[0:1], v[64:65]
	v_pk_mul_f32 v[2:3], v[2:3], v[66:67]
	v_cvt_pk_bf16_f32 v0, v0, v1
	v_cvt_pk_bf16_f32 v1, v2, v3

; #define GAS __attribute__((address_space(1)))
; __device__ __forceinline__ unsigned cvt_pk_bf16(float lo, float hi) { const f32x2 v = {lo, hi}; return __builtin_bit_cast(unsigned, __builtin_convertvector(v, bf16n2)); }
; __device__ __forceinline__ float bf_lo(unsigned u) { return __uint_as_float(u << 16); }
; __device__ __forceinline__ float bf_hi(unsigned u) { return __uint_as_float(u & 0xffff0000u); }
; __device__ __forceinline__ void phase_xn_fused(Frame& F, int l) {
;     ...
;     for (int r = gw; r < MTOT; r += NGW) {
;         if (r >= MP && r < MPAD) { zero_xn_row(XN + (size_t)r * D, lane); continue; }
;         GAS v2u* xb = (GAS v2u*)(HB + (size_t)r * D) + lane; const int pm = r >> 8, rr = r & 255;
;         f32x4 v[4]; float s = 0.f;
; #pragma unroll
;         for (int j = 0; j < 4; ++j) { const int idx = tab[4 * pm + j]; const v2u t = xb[64 * j]; v[j] = (f32x4){bf_lo(t.x), bf_hi(t.x), bf_lo(t.y), bf_hi(t.y)};
;             if (idx >= 0) { v[j] += slab4_sum(sl + (size_t)(4 * idx) * 65536 + (size_t)rr * 256 + 4 * lane); v2u o; o.x = cvt_pk_bf16(v[j][0], v[j][1]); o.y = cvt_pk_bf16(v[j][2], v[j][3]); xb[64 * j] = o; }
.LBB0_112:
	s_and_b32 s14, s13, 0xffffff80
	s_cmpk_lg_i32 s14, 0x4080
	s_mov_b64 s[34:35], -1
	s_cbranch_scc0 .LBB0_122
	v_add_co_u32_e32 v42, vcc, 0xfb700000, v6
	s_ashr_i32 s14, s13, 6
	s_nop 0
	v_addc_co_u32_e32 v43, vcc, -1, v7, vcc
	global_load_dwordx2 v[8:9], v[42:43], off offset:-1024
	global_load_dwordx2 v[46:47], v[42:43], off offset:-512
	global_load_dwordx2 v[48:49], v[42:43], off
	global_load_dwordx2 v[50:51], v[42:43], off offset:512
	global_load_dwordx4 v[52:55], v[4:5], off
	global_load_dwordx4 v[56:59], v[4:5], off offset:1024
	global_load_dwordx4 v[60:63], v[4:5], off offset:2048
	global_load_dwordx4 v[64:67], v[4:5], off offset:3072
	s_lshl_b32 s14, s14, 2
	s_and_b32 s14, s14, -16
	s_add_i32 s14, s14, 0
	v_mov_b32_e32 v10, s14
	ds_read_b32 v12, v10
	s_and_b32 s15, s12, 0xff00
	s_lshl_b32 s20, s15, 1
	v_lshl_add_u64 v[20:21], v[0:1], 0, s[20:21]
	s_waitcnt lgkmcnt(0)
	v_cmp_gt_i32_e32 vcc, 0, v12
	s_and_b64 vcc, exec, vcc
	s_waitcnt vmcnt(7)
	v_lshlrev_b32_e32 v10, 16, v8
	v_and_b32_e32 v11, 0xffff0000, v8
	v_lshlrev_b32_e32 v8, 16, v9
	v_and_b32_e32 v9, 0xffff0000, v9
	s_cbranch_vccnz .LBB0_115
	v_lshlrev_b32_e32 v172, 2, v12
	v_lshlrev_b64 v[12:13], 17, v[172:173]
	v_lshl_add_u64 v[12:13], v[20:21], 0, v[12:13]
	v_add_co_u32_e32 v16, vcc, 0x20000, v12
	global_load_dwordx2 v[14:15], v[12:13], off
	s_nop 0
	v_addc_co_u32_e32 v17, vcc, 0, v13, vcc
	v_add_co_u32_e32 v18, vcc, 0x40000, v12
	global_load_dwordx2 v[16:17], v[16:17], off
	s_nop 0
	v_addc_co_u32_e32 v19, vcc, 0, v13, vcc
	v_add_co_u32_e32 v12, vcc, 0x60000, v12
	global_load_dwordx2 v[18:19], v[18:19], off
	s_nop 0
	v_addc_co_u32_e32 v13, vcc, 0, v13, vcc
	global_load_dwordx2 v[12:13], v[12:13], off
	s_mov_b32 s16, 0xfb6ffc00
	s_mov_b32 s17, -1
	v_lshl_add_u64 v[22:23], v[6:7], 0, s[16:17]
	s_waitcnt vmcnt(3)
	v_lshlrev_b32_e32 v24, 16, v14
	v_and_b32_e32 v25, 0xffff0000, v14
	v_lshlrev_b32_e32 v14, 16, v15
	v_and_b32_e32 v15, 0xffff0000, v15
	s_waitcnt vmcnt(2)
	v_lshlrev_b32_e32 v26, 16, v16
	v_and_b32_e32 v27, 0xffff0000, v16
	v_lshlrev_b32_e32 v16, 16, v17
	v_and_b32_e32 v17, 0xffff0000, v17
	v_pk_add_f32 v[14:15], v[14:15], v[16:17]
	v_pk_add_f32 v[16:17], v[24:25], v[26:27]
	s_waitcnt vmcnt(1)
	v_lshlrev_b32_e32 v24, 16, v18
	v_and_b32_e32 v25, 0xffff0000, v18
	v_lshlrev_b32_e32 v18, 16, v19
	v_and_b32_e32 v19, 0xffff0000, v19
	s_waitcnt vmcnt(0)
	v_lshlrev_b32_e32 v26, 16, v12
	v_and_b32_e32 v27, 0xffff0000, v12
	v_lshlrev_b32_e32 v12, 16, v13
	v_and_b32_e32 v13, 0xffff0000, v13
	v_pk_add_f32 v[12:13], v[18:19], v[12:13]
	v_pk_add_f32 v[18:19], v[24:25], v[26:27]
	v_pk_add_f32 v[12:13], v[14:15], v[12:13]
	v_pk_add_f32 v[16:17], v[16:17], v[18:19]
	v_pk_add_f32 v[8:9], v[8:9], v[12:13]
	v_pk_add_f32 v[10:11], v[10:11], v[16:17]
	v_cvt_pk_bf16_f32 v13, v8, v9
	v_cvt_pk_bf16_f32 v12, v10, v11
	global_store_dwordx2 v[22:23], v[12:13], off
.LBB0_115:
	v_mov_b32_e32 v14, s14
	ds_read_b32 v16, v14 offset:4
	s_waitcnt lgkmcnt(0)
	v_cmp_gt_i32_e32 vcc, 0, v16
	s_and_b64 vcc, exec, vcc
	s_waitcnt vmcnt(6)
	v_lshlrev_b32_e32 v14, 16, v46
	v_and_b32_e32 v15, 0xffff0000, v46
	v_lshlrev_b32_e32 v12, 16, v47
	v_and_b32_e32 v13, 0xffff0000, v47
	s_cbranch_vccnz .LBB0_117
	v_lshlrev_b32_e32 v172, 2, v16
	v_lshlrev_b64 v[16:17], 17, v[172:173]
	v_lshl_add_u64 v[16:17], v[20:21], 0, v[16:17]
	v_add_co_u32_e32 v22, vcc, 0x20000, v16
	global_load_dwordx2 v[18:19], v[16:17], off
	s_nop 0
	v_addc_co_u32_e32 v23, vcc, 0, v17, vcc
	v_add_co_u32_e32 v24, vcc, 0x40000, v16
	global_load_dwordx2 v[22:23], v[22:23], off
	s_nop 0
	v_addc_co_u32_e32 v25, vcc, 0, v17, vcc
	v_add_co_u32_e32 v16, vcc, 0x60000, v16
	global_load_dwordx2 v[24:25], v[24:25], off
	s_nop 0
	v_addc_co_u32_e32 v17, vcc, 0, v17, vcc
	global_load_dwordx2 v[16:17], v[16:17], off
	s_mov_b32 s16, 0xfb6ffe00
	s_mov_b32 s17, -1
	v_lshl_add_u64 v[26:27], v[6:7], 0, s[16:17]
	s_waitcnt vmcnt(3)
	v_lshlrev_b32_e32 v28, 16, v18
	v_and_b32_e32 v29, 0xffff0000, v18
	v_lshlrev_b32_e32 v18, 16, v19
	v_and_b32_e32 v19, 0xffff0000, v19
	s_waitcnt vmcnt(2)
	v_lshlrev_b32_e32 v30, 16, v22
	v_and_b32_e32 v31, 0xffff0000, v22
	v_lshlrev_b32_e32 v22, 16, v23
	v_and_b32_e32 v23, 0xffff0000, v23
	v_pk_add_f32 v[18:19], v[18:19], v[22:23]
	v_pk_add_f32 v[22:23], v[28:29], v[30:31]
	s_waitcnt vmcnt(1)
	v_lshlrev_b32_e32 v28, 16, v24
	v_and_b32_e32 v29, 0xffff0000, v24
	v_lshlrev_b32_e32 v24, 16, v25
	v_and_b32_e32 v25, 0xffff0000, v25
	s_waitcnt vmcnt(0)
	v_lshlrev_b32_e32 v30, 16, v16
	v_and_b32_e32 v31, 0xffff0000, v16
	v_lshlrev_b32_e32 v16, 16, v17
	v_and_b32_e32 v17, 0xffff0000, v17
	v_pk_add_f32 v[16:17], v[24:25], v[16:17]
	v_pk_add_f32 v[24:25], v[28:29], v[30:31]
	v_pk_add_f32 v[16:17], v[18:19], v[16:17]
	v_pk_add_f32 v[22:23], v[22:23], v[24:25]
	v_pk_add_f32 v[12:13], v[12:13], v[16:17]
	v_pk_add_f32 v[14:15], v[14:15], v[22:23]
	v_cvt_pk_bf16_f32 v17, v12, v13
	v_cvt_pk_bf16_f32 v16, v14, v15
	global_store_dwordx2 v[26:27], v[16:17], off
; __device__ __forceinline__ unsigned cvt_pk_bf16(float lo, float hi) { const f32x2 v = {lo, hi}; return __builtin_bit_cast(unsigned, __builtin_convertvector(v, bf16n2)); }
; __device__ __forceinline__ float bf_lo(unsigned u) { return __uint_as_float(u << 16); }
; __device__ __forceinline__ float bf_hi(unsigned u) { return __uint_as_float(u & 0xffff0000u); }
; __device__ __forceinline__ void phase_xn_fused(Frame& F, int l) {
;     ...
;         f32x4 v[4]; float s = 0.f;
; #pragma unroll
;         for (int j = 0; j < 4; ++j) { const int idx = tab[4 * pm + j]; const v2u t = xb[64 * j]; v[j] = (f32x4){bf_lo(t.x), bf_hi(t.x), bf_lo(t.y), bf_hi(t.y)};
;             if (idx >= 0) { v[j] += slab4_sum(sl + (size_t)(4 * idx) * 65536 + (size_t)rr * 256 + 4 * lane); v2u o; o.x = cvt_pk_bf16(v[j][0], v[j][1]); o.y = cvt_pk_bf16(v[j][2], v[j][3]); xb[64 * j] = o; }
.LBB0_117:
	v_mov_b32_e32 v18, s14
	ds_read_b32 v22, v18 offset:8
	s_waitcnt lgkmcnt(0)
	v_cmp_gt_i32_e32 vcc, 0, v22
	s_and_b64 vcc, exec, vcc
	s_waitcnt vmcnt(5)
	v_lshlrev_b32_e32 v18, 16, v48
	v_and_b32_e32 v19, 0xffff0000, v48
	v_lshlrev_b32_e32 v16, 16, v49
	v_and_b32_e32 v17, 0xffff0000, v49
	s_cbranch_vccnz .LBB0_119
	v_lshlrev_b32_e32 v172, 2, v22
	v_lshlrev_b64 v[22:23], 17, v[172:173]
	v_lshl_add_u64 v[22:23], v[20:21], 0, v[22:23]
	v_add_co_u32_e32 v26, vcc, 0x20000, v22
	global_load_dwordx2 v[24:25], v[22:23], off
	s_nop 0
	v_addc_co_u32_e32 v27, vcc, 0, v23, vcc
	v_add_co_u32_e32 v28, vcc, 0x40000, v22
	global_load_dwordx2 v[26:27], v[26:27], off
	s_nop 0
	v_addc_co_u32_e32 v29, vcc, 0, v23, vcc
	v_add_co_u32_e32 v22, vcc, 0x60000, v22
	global_load_dwordx2 v[28:29], v[28:29], off
	s_nop 0
	v_addc_co_u32_e32 v23, vcc, 0, v23, vcc
	global_load_dwordx2 v[22:23], v[22:23], off
	s_mov_b32 s16, 0xfb700000
	s_mov_b32 s17, -1
	v_lshl_add_u64 v[30:31], v[6:7], 0, s[16:17]
	s_waitcnt vmcnt(3)
	v_lshlrev_b32_e32 v32, 16, v24
	v_and_b32_e32 v33, 0xffff0000, v24
	v_lshlrev_b32_e32 v24, 16, v25
	v_and_b32_e32 v25, 0xffff0000, v25
	s_waitcnt vmcnt(2)
	v_lshlrev_b32_e32 v34, 16, v26
	v_and_b32_e32 v35, 0xffff0000, v26
	v_lshlrev_b32_e32 v26, 16, v27
	v_and_b32_e32 v27, 0xffff0000, v27
	v_pk_add_f32 v[24:25], v[24:25], v[26:27]
	v_pk_add_f32 v[26:27], v[32:33], v[34:35]
	s_waitcnt vmcnt(1)
	v_lshlrev_b32_e32 v32, 16, v28
	v_and_b32_e32 v33, 0xffff0000, v28
	v_lshlrev_b32_e32 v28, 16, v29
	v_and_b32_e32 v29, 0xffff0000, v29
	s_waitcnt vmcnt(0)
	v_lshlrev_b32_e32 v34, 16, v22
	v_and_b32_e32 v35, 0xffff0000, v22
	v_lshlrev_b32_e32 v22, 16, v23
	v_and_b32_e32 v23, 0xffff0000, v23
	v_pk_add_f32 v[22:23], v[28:29], v[22:23]
	v_pk_add_f32 v[28:29], v[32:33], v[34:35]
	v_pk_add_f32 v[22:23], v[24:25], v[22:23]
	v_pk_add_f32 v[26:27], v[26:27], v[28:29]
	v_pk_add_f32 v[16:17], v[16:17], v[22:23]
	v_pk_add_f32 v[18:19], v[18:19], v[26:27]
	v_cvt_pk_bf16_f32 v23, v16, v17
	v_cvt_pk_bf16_f32 v22, v18, v19
	global_store_dwordx2 v[30:31], v[22:23], off
.LBB0_119:
	v_mov_b32_e32 v24, s14
	ds_read_b32 v26, v24 offset:12
	s_waitcnt lgkmcnt(0)
	v_cmp_gt_i32_e32 vcc, 0, v26
	s_and_b64 vcc, exec, vcc
	s_waitcnt vmcnt(4)
	v_lshlrev_b32_e32 v24, 16, v50
	v_and_b32_e32 v25, 0xffff0000, v50
	v_lshlrev_b32_e32 v22, 16, v51
	v_and_b32_e32 v23, 0xffff0000, v51
	s_cbranch_vccnz .LBB0_121
	v_lshlrev_b32_e32 v172, 2, v26
	v_lshlrev_b64 v[26:27], 17, v[172:173]
	v_lshl_add_u64 v[20:21], v[20:21], 0, v[26:27]
	v_add_co_u32_e32 v28, vcc, 0x20000, v20
	global_load_dwordx2 v[26:27], v[20:21], off
	s_nop 0
	v_addc_co_u32_e32 v29, vcc, 0, v21, vcc
	v_add_co_u32_e32 v30, vcc, 0x40000, v20
	global_load_dwordx2 v[28:29], v[28:29], off
	s_nop 0
	v_addc_co_u32_e32 v31, vcc, 0, v21, vcc
	v_add_co_u32_e32 v20, vcc, 0x60000, v20
	global_load_dwordx2 v[30:31], v[30:31], off
	s_nop 0
	v_addc_co_u32_e32 v21, vcc, 0, v21, vcc
	global_load_dwordx2 v[20:21], v[20:21], off
	s_mov_b32 s14, 0xfb700200
	s_mov_b32 s15, -1
	v_lshl_add_u64 v[32:33], v[6:7], 0, s[14:15]
	s_waitcnt vmcnt(3)
	v_lshlrev_b32_e32 v34, 16, v26
	v_and_b32_e32 v35, 0xffff0000, v26
	v_lshlrev_b32_e32 v26, 16, v27
	v_and_b32_e32 v27, 0xffff0000, v27
	s_waitcnt vmcnt(2)
	v_lshlrev_b32_e32 v36, 16, v28
	v_and_b32_e32 v37, 0xffff0000, v28
	v_lshlrev_b32_e32 v28, 16, v29
	v_and_b32_e32 v29, 0xffff0000, v29
	v_pk_add_f32 v[26:27], v[26:27], v[28:29]
	v_pk_add_f32 v[28:29], v[34:35], v[36:37]
	s_waitcnt vmcnt(1)
	v_lshlrev_b32_e32 v34, 16, v30
	v_and_b32_e32 v35, 0xffff0000, v30
	v_lshlrev_b32_e32 v30, 16, v31
	v_and_b32_e32 v31, 0xffff0000, v31
	s_waitcnt vmcnt(0)
	v_lshlrev_b32_e32 v36, 16, v20
	v_and_b32_e32 v37, 0xffff0000, v20
	v_lshlrev_b32_e32 v20, 16, v21
	v_and_b32_e32 v21, 0xffff0000, v21
	v_pk_add_f32 v[20:21], v[30:31], v[20:21]
	v_pk_add_f32 v[30:31], v[34:35], v[36:37]
	v_pk_add_f32 v[20:21], v[26:27], v[20:21]
	v_pk_add_f32 v[28:29], v[28:29], v[30:31]
	v_pk_add_f32 v[22:23], v[22:23], v[20:21]
	v_pk_add_f32 v[24:25], v[24:25], v[28:29]
	v_cvt_pk_bf16_f32 v21, v22, v23
	v_cvt_pk_bf16_f32 v20, v24, v25
	global_store_dwordx2 v[32:33], v[20:21], off
; #define GAS __attribute__((address_space(1)))
; __device__ __forceinline__ unsigned cvt_pk_bf16(float lo, float hi) { const f32x2 v = {lo, hi}; return __builtin_bit_cast(unsigned, __builtin_convertvector(v, bf16n2)); }
; __device__ __forceinline__ float frsq(float x) { return __builtin_amdgcn_rsqf(x); }
; __device__ __forceinline__ void phase_xn_fused(Frame& F, int l) {
;     ...
;             s += (v[j].x * v[j].x + v[j].y * v[j].y) + (v[j].z * v[j].z + v[j].w * v[j].w); }
;         const float rs = frsq(wave_sum(s) * (1.f / D) + EPS);
;         GAS v2u* o8 = (GAS v2u*)(XN + (size_t)r * D) + lane;
; #pragma unroll
;         for (int j = 0; j < 4; ++j) { const f32x4 gg = ((const GAS f32x4*)gn)[lane + 64 * j]; v2u o; o.x = cvt_pk_bf16(v[j].x * rs * gg.x, v[j].y * rs * gg.y); o.y = cvt_pk_bf16(v[j].z * rs * gg.z, v[j].w * rs * gg.w); o8[64 * j] = o; }
.LBB0_121:
	v_mul_f32_e32 v34, v11, v11
	v_mul_f32_e32 v35, v9, v9
	v_mul_f32_e32 v36, v15, v15
	v_mul_f32_e32 v37, v13, v13
	v_and_b32_e32 v40, 64, v214
	v_mul_f32_e32 v38, v19, v19
	v_mul_f32_e32 v39, v17, v17
	v_pk_mul_f32 v[20:21], v[22:23], v[22:23]
	v_pk_mul_f32 v[30:31], v[24:25], v[24:25]
	v_xor_b32_e32 v41, 1, v214
	v_fmac_f32_e32 v34, v10, v10
	v_fmac_f32_e32 v35, v8, v8
	v_fmac_f32_e32 v36, v14, v14
	v_fmac_f32_e32 v37, v12, v12
	v_add_u32_e32 v40, 64, v40
	v_fmac_f32_e32 v38, v18, v18
	v_fmac_f32_e32 v39, v16, v16
	v_pk_mov_b32 v[32:33], v[30:31], v[20:21] op_sel:[1,0]
	v_mov_b32_e32 v31, v21
	v_add_f32_e32 v34, v34, v35
	v_add_f32_e32 v35, v36, v37
	v_cmp_lt_i32_e32 vcc, v41, v40
	v_add_f32_e32 v36, v38, v39
	v_pk_add_f32 v[20:21], v[32:33], v[30:31]
	v_cndmask_b32_e32 v30, v214, v41, vcc
	v_add_f32_e32 v31, v34, v35
	v_add_f32_e32 v20, v20, v21
	v_lshlrev_b32_e32 v21, 2, v30
	v_add_f32_e32 v30, v31, v36
	v_add_f32_e32 v20, v30, v20
	ds_bpermute_b32 v21, v21, v20
	v_xor_b32_e32 v30, 2, v214
	v_cmp_lt_i32_e32 vcc, v30, v40
	s_mov_b64 s[34:35], 0
	s_waitcnt lgkmcnt(0)
	v_add_f32_e32 v20, v20, v21
	v_cndmask_b32_e32 v30, v214, v30, vcc
	v_lshlrev_b32_e32 v30, 2, v30
	ds_bpermute_b32 v21, v30, v20
	v_xor_b32_e32 v30, 4, v214
	v_cmp_lt_i32_e32 vcc, v30, v40
	s_waitcnt lgkmcnt(0)
	v_add_f32_e32 v20, v20, v21
	v_cndmask_b32_e32 v30, v214, v30, vcc
	v_lshlrev_b32_e32 v30, 2, v30
	ds_bpermute_b32 v21, v30, v20
	v_xor_b32_e32 v30, 8, v214
	v_cmp_lt_i32_e32 vcc, v30, v40
	s_waitcnt lgkmcnt(0)
	v_add_f32_e32 v20, v20, v21
	v_cndmask_b32_e32 v30, v214, v30, vcc
	v_lshlrev_b32_e32 v30, 2, v30
	ds_bpermute_b32 v21, v30, v20
	v_xor_b32_e32 v30, 16, v214
	v_cmp_lt_i32_e32 vcc, v30, v40
	s_waitcnt lgkmcnt(0)
	v_add_f32_e32 v20, v20, v21
	v_cndmask_b32_e32 v30, v214, v30, vcc
	v_lshlrev_b32_e32 v30, 2, v30
	ds_bpermute_b32 v21, v30, v20
	v_xor_b32_e32 v30, 32, v214
	v_cmp_lt_i32_e32 vcc, v30, v40
	s_waitcnt lgkmcnt(0)
	v_add_f32_e32 v20, v20, v21
	v_cndmask_b32_e32 v30, v214, v30, vcc
	v_lshlrev_b32_e32 v30, 2, v30
	ds_bpermute_b32 v21, v30, v20
	s_waitcnt lgkmcnt(0)
	v_add_f32_e32 v20, v20, v21
	v_fmamk_f32 v20, v20, 0x3a800000, v212
	v_rsq_f32_e32 v20, v20
	s_nop 0
	v_pk_mul_f32 v[10:11], v[10:11], v[20:21] op_sel_hi:[1,0]
	v_pk_mul_f32 v[8:9], v[8:9], v[20:21] op_sel_hi:[1,0]
	s_waitcnt vmcnt(0)
	v_pk_mul_f32 v[10:11], v[52:53], v[10:11]
	v_pk_mul_f32 v[8:9], v[54:55], v[8:9]
	v_cvt_pk_bf16_f32 v10, v10, v11
	v_cvt_pk_bf16_f32 v11, v8, v9
	global_store_dwordx2 v[6:7], v[10:11], off offset:-1024
	v_pk_mul_f32 v[14:15], v[14:15], v[20:21] op_sel_hi:[1,0]
	v_pk_mul_f32 v[12:13], v[12:13], v[20:21] op_sel_hi:[1,0]
	v_pk_mul_f32 v[8:9], v[56:57], v[14:15]
	v_pk_mul_f32 v[10:11], v[58:59], v[12:13]
	v_cvt_pk_bf16_f32 v8, v8, v9
	v_cvt_pk_bf16_f32 v9, v10, v11
	global_store_dwordx2 v[6:7], v[8:9], off offset:-512
	v_pk_mul_f32 v[12:13], v[18:19], v[20:21] op_sel_hi:[1,0]
	v_pk_mul_f32 v[14:15], v[16:17], v[20:21] op_sel_hi:[1,0]
	v_pk_mul_f32 v[8:9], v[60:61], v[12:13]
	v_pk_mul_f32 v[10:11], v[62:63], v[14:15]
	v_cvt_pk_bf16_f32 v8, v8, v9
	v_cvt_pk_bf16_f32 v9, v10, v11
	global_store_dwordx2 v[6:7], v[8:9], off
	v_pk_mul_f32 v[12:13], v[24:25], v[20:21] op_sel_hi:[1,0]
	v_pk_mul_f32 v[14:15], v[22:23], v[20:21] op_sel_hi:[1,0]
	v_pk_mul_f32 v[8:9], v[12:13], v[64:65]
	v_pk_mul_f32 v[10:11], v[14:15], v[66:67]
	v_cvt_pk_bf16_f32 v8, v8, v9
	v_cvt_pk_bf16_f32 v9, v10, v11
